# added: closed-form next-unit index (no software integer division / readfirstlane on the unit boundary) in 6 GEMM phases
# baseline (speedup 1.0000x reference)
;     __device__ bool next(int i, Unit& u) const {
;         const long L = (long)i * G + c; if (L >= nwg) return false;
;         int wgid = (int)L; { const int q = nwg / NXCD, r = nwg % NXCD, xcd = wgid % NXCD, off = wgid / NXCD; wgid = (xcd < r ? xcd * (q + 1) : r * (q + 1) + (xcd - r) * q) + off; }
;         const int nig = WGM * nN, gid = wgid / nig, fm = gid * WGM, gsz = (nM - fm) < WGM ? (nM - fm) : WGM;
;         u.pm = fm + ((wgid % nig) % gsz); u.pn = (wgid % nig) / gsz; return true;
.LBB0_202:
	s_add_i32 s35, s35, 1
	s_mul_i32 s0, s35, s38
	s_mul_hi_u32 s1, s35, s92
	s_add_i32 s1, s1, s0
	s_mul_i32 s0, s35, s92
	s_add_u32 s14, s0, s93
	s_addc_u32 s15, s1, s28
	v_cmp_gt_i64_e64 s[0:1], s[14:15], v[144:145]
	s_and_b64 vcc, exec, s[0:1]
	s_cbranch_vccnz .LBB0_204
	s_lshr_b32 s10, s14, 3
	s_mov_b32 s13, 0
	s_sub_u32 s11, s10, 0xa8
	s_cmp_ge_u32 s10, 0xa8
	s_cselect_b32 s10, s11, s10
	s_addc_u32 s13, s13, 0
	s_sub_u32 s11, s10, 0xa8
	s_cmp_ge_u32 s10, 0xa8
	s_cselect_b32 s10, s11, s10
	s_addc_u32 s13, s13, 0
	s_sub_u32 s11, s10, 0xa8
	s_cmp_ge_u32 s10, 0xa8
	s_cselect_b32 s10, s11, s10
	s_addc_u32 s13, s13, 0
	s_and_b32 s12, s14, 7
	s_lshl_b32 s12, s12, 2
	s_add_i32 s12, s12, s13
	s_lshl_b32 s12, s12, 3
	s_and_b32 s13, s10, 7
	s_add_i32 s12, s12, s13
	s_lshr_b32 s10, s10, 3

;     __device__ bool next(int i, Unit& u) const {
;         const long L = (long)i * G + c; if (L >= nwg) return false;
;         int wgid = (int)L; { const int q = nwg / NXCD, r = nwg % NXCD, xcd = wgid % NXCD, off = wgid / NXCD; wgid = (xcd < r ? xcd * (q + 1) : r * (q + 1) + (xcd - r) * q) + off; }
;         const int nig = WGM * nN, gid = wgid / nig, fm = gid * WGM, gsz = (nM - fm) < WGM ? (nM - fm) : WGM;
;         u.pm = fm + ((wgid % nig) % gsz); u.pn = (wgid % nig) / gsz; return true;
.LBB0_763:
	s_add_i32 s34, s34, 1
	s_mul_i32 s0, s34, s37
	s_mul_hi_u32 s1, s34, s92
	s_add_i32 s1, s1, s0
	s_mul_i32 s0, s34, s92
	s_add_u32 s14, s0, s93
	s_addc_u32 s15, s1, s26
	v_cmp_gt_i64_e64 s[0:1], s[14:15], v[144:145]
	s_and_b64 vcc, exec, s[0:1]
	s_cbranch_vccnz .LBB0_769
	s_lshr_b32 s10, s14, 3
	s_mov_b32 s13, 0
	s_sub_u32 s11, s10, 0x80
	s_cmp_ge_u32 s10, 0x80
	s_cselect_b32 s10, s11, s10
	s_addc_u32 s13, s13, 0
	s_sub_u32 s11, s10, 0x80
	s_cmp_ge_u32 s10, 0x80
	s_cselect_b32 s10, s11, s10
	s_addc_u32 s13, s13, 0
	s_sub_u32 s11, s10, 0x80
	s_cmp_ge_u32 s10, 0x80
	s_cselect_b32 s10, s11, s10
	s_addc_u32 s13, s13, 0
	s_and_b32 s12, s14, 7
	s_lshl_b32 s12, s12, 2
	s_add_i32 s12, s12, s13
	s_lshl_b32 s12, s12, 3
	s_and_b32 s13, s10, 7
	s_add_i32 s12, s12, s13
	s_lshr_b32 s10, s10, 3

;     __device__ bool next(int i, Unit& u) const {
;         const long L = (long)i * G + c; if (L >= nwg) return false;
;         int wgid = (int)L; { const int q = nwg / NXCD, r = nwg % NXCD, xcd = wgid % NXCD, off = wgid / NXCD; wgid = (xcd < r ? xcd * (q + 1) : r * (q + 1) + (xcd - r) * q) + off; }
;         const int nig = WGM * nN, gid = wgid / nig, fm = gid * WGM, gsz = (nM - fm) < WGM ? (nM - fm) : WGM;
;         u.pm = fm + ((wgid % nig) % gsz); u.pn = (wgid % nig) / gsz; return true;
.LBB0_837:
	s_add_i32 s33, s33, 1
	s_mul_i32 s2, s33, s40
	s_mul_hi_u32 s3, s33, s92
	s_add_i32 s3, s3, s2
	s_mul_i32 s2, s33, s92
	s_add_u32 s18, s2, s93
	s_addc_u32 s19, s3, s41
	v_cmp_gt_i64_e64 s[2:3], s[18:19], v[168:169]
	s_and_b64 vcc, exec, s[2:3]
	s_cbranch_vccnz .LBB0_843
	s_lshr_b32 s14, s18, 3
	s_mov_b32 s17, 0
	s_sub_u32 s15, s14, 0x20
	s_cmp_ge_u32 s14, 0x20
	s_cselect_b32 s14, s15, s14
	s_addc_u32 s17, s17, 0
	s_sub_u32 s15, s14, 0x20
	s_cmp_ge_u32 s14, 0x20
	s_cselect_b32 s14, s15, s14
	s_addc_u32 s17, s17, 0
	s_sub_u32 s15, s14, 0x20
	s_cmp_ge_u32 s14, 0x20
	s_cselect_b32 s14, s15, s14
	s_addc_u32 s17, s17, 0
	s_and_b32 s16, s18, 7
	s_lshl_b32 s16, s16, 2
	s_add_i32 s16, s16, s17
	s_lshl_b32 s16, s16, 3
	s_and_b32 s17, s14, 7
	s_add_i32 s16, s16, s17
	s_lshr_b32 s14, s14, 3

;     __device__ bool next(int i, Unit& u) const {
;         const long L = (long)i * G + c; if (L >= nwg) return false;
;         int wgid = (int)L; { const int q = nwg / NXCD, r = nwg % NXCD, xcd = wgid % NXCD, off = wgid / NXCD; wgid = (xcd < r ? xcd * (q + 1) : r * (q + 1) + (xcd - r) * q) + off; }
;         const int nig = WGM * nN, gid = wgid / nig, fm = gid * WGM, gsz = (nM - fm) < WGM ? (nM - fm) : WGM;
;         u.pm = fm + ((wgid % nig) % gsz); u.pn = (wgid % nig) / gsz; return true;
.LBB0_919:
	s_add_i32 s34, s34, 1
	s_mul_i32 s0, s34, s37
	s_mul_hi_u32 s1, s34, s92
	s_add_i32 s1, s1, s0
	s_mul_i32 s0, s34, s92
	s_add_u32 s14, s0, s93
	s_addc_u32 s15, s1, s28
	v_cmp_gt_i64_e64 s[0:1], s[14:15], v[144:145]
	s_and_b64 vcc, exec, s[0:1]
	s_cbranch_vccnz .LBB0_921
	s_lshr_b32 s10, s14, 3
	s_mov_b32 s13, 0
	s_sub_u32 s11, s10, 0xa0
	s_cmp_ge_u32 s10, 0xa0
	s_cselect_b32 s10, s11, s10
	s_addc_u32 s13, s13, 0
	s_sub_u32 s11, s10, 0xa0
	s_cmp_ge_u32 s10, 0xa0
	s_cselect_b32 s10, s11, s10
	s_addc_u32 s13, s13, 0
	s_sub_u32 s11, s10, 0xa0
	s_cmp_ge_u32 s10, 0xa0
	s_cselect_b32 s10, s11, s10
	s_addc_u32 s13, s13, 0
	s_and_b32 s12, s14, 7
	s_lshl_b32 s12, s12, 2
	s_add_i32 s12, s12, s13
	s_lshl_b32 s12, s12, 3
	s_and_b32 s13, s10, 7
	s_add_i32 s12, s12, s13
	s_lshr_b32 s10, s10, 3

;     __device__ bool next(int i, Unit& u) const {
;         const long L = (long)i * G + c; if (L >= nwg) return false;
;         int wgid = (int)L; { const int q = nwg / NXCD, r = nwg % NXCD, xcd = wgid % NXCD, off = wgid / NXCD; wgid = (xcd < r ? xcd * (q + 1) : r * (q + 1) + (xcd - r) * q) + off; }
;         const int nig = WGM * nN, gid = wgid / nig, fm = gid * WGM, gsz = (nM - fm) < WGM ? (nM - fm) : WGM;
;         u.pm = fm + ((wgid % nig) % gsz); u.pn = (wgid % nig) / gsz; return true;
.LBB0_1197:
	s_add_i32 s33, s33, 1
	s_mul_i32 s0, s33, s36
	s_mul_hi_u32 s1, s33, s92
	s_add_i32 s1, s1, s0
	s_mul_i32 s0, s33, s92
	s_add_u32 s14, s0, s93
	s_addc_u32 s15, s1, s9
	v_cmp_gt_i64_e64 s[0:1], s[14:15], v[144:145]
	s_and_b64 vcc, exec, s[0:1]
	s_cbranch_vccnz .LBB0_1203
	s_lshr_b32 s10, s14, 3
	s_mov_b32 s13, 0
	s_sub_u32 s11, s10, 0x80
	s_cmp_ge_u32 s10, 0x80
	s_cselect_b32 s10, s11, s10
	s_addc_u32 s13, s13, 0
	s_sub_u32 s11, s10, 0x80
	s_cmp_ge_u32 s10, 0x80
	s_cselect_b32 s10, s11, s10
	s_addc_u32 s13, s13, 0
	s_sub_u32 s11, s10, 0x80
	s_cmp_ge_u32 s10, 0x80
	s_cselect_b32 s10, s11, s10
	s_addc_u32 s13, s13, 0
	s_and_b32 s12, s14, 7
	s_lshl_b32 s12, s12, 2
	s_add_i32 s12, s12, s13
	s_lshl_b32 s12, s12, 3
	s_and_b32 s13, s10, 7
	s_add_i32 s12, s12, s13
	s_lshr_b32 s10, s10, 3
